# v14 + S5 idle-lane L2 prefetch of u tiles + gdn exact counted waits on double-buffered loads and g/beta issued two chunks ahead
# speedup vs baseline: 1.0011x; 1.0011x over previous
.LBB0_366:
	v_readlane_b32 s0, v255, 33
	s_lshr_b32 s0, s0, 3
	s_cmp_eq_u32 s2, 0
	v_sub_u32_e32 v52, 0, v72
	s_cselect_b64 s[6:7], -1, 0
	s_mulk_i32 s1, 0x7600
	s_add_i32 s1, s1, 0
	s_andn2_b64 vcc, exec, s[8:9]
	v_cndmask_b32_e64 v74, v52, v72, s[6:7]
	s_cbranch_vccnz .LBB0_370
	v_cmp_lt_u32_e64 s[4:5], 31, v69
	v_cndmask_b32_e64 v178, 0, 64, s[4:5]
	v_sub_u32_e32 v179, 0, v178
	v_cndmask_b32_e64 v178, v179, v178, s[6:7]
	v_add_u32_e32 v178, v178, v74
	s_lshl_b32 s2, s0, 8
	s_and_b64 s[4:5], s[6:7], exec
	s_cselect_b32 s4, 0, 0xff
	s_or_b32 s11, s4, s2
	s_lshl_b32 s10, s14, 4
	v_cmp_gt_u32_e32 vcc, 32, v69
	s_and_saveexec_b64 s[4:5], vcc
	s_cbranch_execz .LBB0_369
	v_add_u32_e32 v52, s11, v74
	v_mul_u32_u24_e32 v52, 0xe00, v52
	v_or_b32_e32 v52, s10, v52
	s_movk_i32 s11, 0xd00
	v_add3_u32 v52, v52, v75, s11
	v_ashrrev_i32_e32 v53, 31, v52
	v_lshl_add_u64 v[52:53], v[52:53], 1, s[82:83]
	global_load_dwordx4 v[52:55], v[52:53], off
	v_lshlrev_b32_e32 v56, 5, v72
	v_and_b32_e32 v57, 48, v68
	v_add3_u32 v56, s1, v56, v57
	s_waitcnt vmcnt(0)
	ds_write_b128 v56, v[52:55] offset:29184

.LBB0_372:
	s_or_b64 exec, exec, s[4:5]
	s_min_u32 s4, s10, 0x10a
	s_lshl_b32 s4, s4, 4
	s_cmp_lt_u32 s10, 11
	s_movk_i32 s5, 0xff50
	s_movk_i32 s10, 0xaf
	s_cselect_b32 s5, 0x50, s5
	s_cselect_b32 s10, s10, 0x10af
	s_cselect_b32 s11, s8, s2
	s_add_i32 s12, s4, s5
	s_sub_i32 s10, s10, s4
	s_and_b64 s[4:5], s[6:7], exec
	s_cselect_b32 s4, s12, s10
	s_add_i32 s4, s4, s11
	v_add_u32_e32 v60, s4, v178
	v_max_i32_e32 v60, 0, v60
	v_mad_u32_u24 v60, v60, s63, v82
	v_ashrrev_i32_e32 v61, 31, v60
	v_lshl_add_u64 v[60:61], v[60:61], 1, s[82:83]
	global_load_dwordx4 v[60:63], v[60:61], off

.LBB0_376:
	s_or_b64 exec, exec, s[4:5]
	s_add_i32 s9, s10, 4
	s_min_u32 s4, s9, 0x10a
	s_lshl_b32 s4, s4, 4
	s_cmp_lt_u32 s9, 11
	s_movk_i32 s5, 0xff50
	s_movk_i32 s11, 0xaf
	s_cselect_b32 s5, 0x50, s5
	s_cselect_b32 s11, s11, 0x10af
	s_cselect_b32 s12, s8, s2
	s_add_i32 s13, s4, s5
	s_sub_i32 s11, s11, s4
	s_and_b64 s[4:5], s[6:7], exec
	s_cselect_b32 s4, s13, s11
	s_add_i32 s4, s4, s12
	s_waitcnt vmcnt(3)
	v_add_u32_e32 v52, s4, v178
	v_max_i32_e32 v52, 0, v52
	v_mad_u32_u24 v52, v52, s63, v82
	v_ashrrev_i32_e32 v53, 31, v52
	v_lshl_add_u64 v[52:53], v[52:53], 1, s[82:83]
	global_load_dwordx4 v[52:55], v[52:53], off
	s_add_i32 s4, s10, 3
	s_cmpk_gt_u32 s4, 0x10f
	v_xor_b32_e32 v75, 0x80000000, v71
	v_add_u32_e32 v88, 0x6000, v87
	v_add_u32_e32 v86, 0x6200, v87
	v_add_u32_e32 v81, 0x6400, v87
	v_add_u32_e32 v80, 0x6600, v87
	v_add_u32_e32 v79, 0x6800, v87
	v_add_u32_e32 v78, 0x6a00, v87
	v_add_u32_e32 v77, 0x6c00, v87
	v_add_u32_e32 v76, 0x6e00, v87
	s_cbranch_scc1 .LBB0_378
	ds_read_b128 v[92:95], v83 offset:15360
	ds_read_b128 v[96:99], v83 offset:15376
	ds_read_b128 v[100:103], v83 offset:10240
	ds_read_b128 v[104:107], v83 offset:10256
	ds_read_b128 v[108:111], v83 offset:10272
	ds_read_b128 v[112:115], v83 offset:10288
	ds_read_b128 v[116:119], v83 offset:15392
	ds_read_b128 v[120:123], v83 offset:15408
	s_waitcnt lgkmcnt(7)
	v_fma_f32 v92, v71, v89, v92
	s_waitcnt lgkmcnt(5)
	v_fma_f32 v91, v75, v90, v100
	s_waitcnt lgkmcnt(0)
	v_fma_f32 v89, v70, v89, v91
	v_fma_f32 v90, v70, v90, v92
	v_fma_f32 v92, v75, v90, v101
	v_cvt_pk_bf16_f32 v91, v89, v90
	v_fma_f32 v93, v71, v89, v93
	v_fma_f32 v89, v70, v89, v92
	v_fma_f32 v90, v70, v90, v93
	v_cvt_pk_bf16_f32 v92, v89, v90
	ds_write2_b32 v88, v91, v92 offset0:64 offset1:132
	v_fma_f32 v92, v71, v89, v94
	v_fma_f32 v91, v75, v90, v102
	v_fma_f32 v89, v70, v89, v91
	v_fma_f32 v90, v70, v90, v92
	v_fma_f32 v92, v75, v90, v103
	v_cvt_pk_bf16_f32 v91, v89, v90
	v_fma_f32 v93, v71, v89, v95
	v_fma_f32 v89, v70, v89, v92
	v_fma_f32 v90, v70, v90, v93
	v_cvt_pk_bf16_f32 v92, v89, v90
	ds_write2_b32 v86, v91, v92 offset0:72 offset1:140
	v_fma_f32 v92, v71, v89, v96
	s_waitcnt lgkmcnt(6)
	v_fma_f32 v91, v75, v90, v104
	v_fma_f32 v89, v70, v89, v91
	v_fma_f32 v90, v70, v90, v92
	v_fma_f32 v92, v75, v90, v105
	v_cvt_pk_bf16_f32 v91, v89, v90
	v_fma_f32 v93, v71, v89, v97
	v_fma_f32 v89, v70, v89, v92
	v_fma_f32 v90, v70, v90, v93
	v_cvt_pk_bf16_f32 v92, v89, v90
	ds_write2_b32 v81, v91, v92 offset0:80 offset1:148
	v_fma_f32 v92, v71, v89, v98
	v_fma_f32 v91, v75, v90, v106
	v_fma_f32 v89, v70, v89, v91
	v_fma_f32 v90, v70, v90, v92
	v_fma_f32 v92, v75, v90, v107
	v_cvt_pk_bf16_f32 v91, v89, v90
	v_fma_f32 v93, v71, v89, v99
	v_fma_f32 v89, v70, v89, v92
	v_fma_f32 v90, v70, v90, v93
	v_cvt_pk_bf16_f32 v92, v89, v90
	ds_write2_b32 v80, v91, v92 offset0:88 offset1:156
	s_waitcnt lgkmcnt(5)
	v_fma_f32 v92, v71, v89, v116
	v_fma_f32 v91, v75, v90, v108
	v_fma_f32 v89, v70, v89, v91
	v_fma_f32 v90, v70, v90, v92
	v_fma_f32 v92, v75, v90, v109
	v_cvt_pk_bf16_f32 v91, v89, v90
	v_fma_f32 v93, v71, v89, v117
	v_fma_f32 v89, v70, v89, v92
	v_fma_f32 v90, v70, v90, v93
	v_cvt_pk_bf16_f32 v92, v89, v90
	ds_write2_b32 v79, v91, v92 offset0:96 offset1:164
	v_fma_f32 v92, v71, v89, v118
	v_fma_f32 v91, v75, v90, v110
	v_fma_f32 v89, v70, v89, v91
	v_fma_f32 v90, v70, v90, v92
	v_fma_f32 v92, v75, v90, v111
	v_cvt_pk_bf16_f32 v91, v89, v90
	v_fma_f32 v93, v71, v89, v119
	v_fma_f32 v89, v70, v89, v92
	v_fma_f32 v90, v70, v90, v93
	v_cvt_pk_bf16_f32 v92, v89, v90
	ds_write2_b32 v78, v91, v92 offset0:104 offset1:172
	s_waitcnt lgkmcnt(6)
	v_fma_f32 v92, v71, v89, v120
	v_fma_f32 v91, v75, v90, v112
	v_fma_f32 v89, v70, v89, v91
	v_fma_f32 v90, v70, v90, v92
	v_fma_f32 v92, v75, v90, v113
	v_cvt_pk_bf16_f32 v91, v89, v90
	v_fma_f32 v93, v71, v89, v121
	v_fma_f32 v89, v70, v89, v92
	v_fma_f32 v90, v70, v90, v93
	v_cvt_pk_bf16_f32 v92, v89, v90
	ds_write2_b32 v77, v91, v92 offset0:112 offset1:180
	v_fma_f32 v92, v71, v89, v122
	v_fma_f32 v91, v75, v90, v114
	v_fma_f32 v89, v70, v89, v91
	v_fma_f32 v90, v70, v90, v92
	v_fma_f32 v92, v75, v90, v115
	v_cvt_pk_bf16_f32 v91, v89, v90
	v_fma_f32 v93, v71, v89, v123
	v_fma_f32 v89, v70, v89, v92
	v_fma_f32 v90, v70, v90, v93
	v_cvt_pk_bf16_f32 v92, v89, v90
	ds_write2_b32 v76, v91, v92 offset0:120 offset1:188
.LBB0_378:
	s_waitcnt lgkmcnt(0)
	s_barrier
	s_and_saveexec_b64 s[4:5], vcc
	v_add_u32_e32 v91, v84, v85
	s_waitcnt vmcnt(3)
	ds_write_b128 v91, v[56:59] offset:29184
	s_or_b64 exec, exec, s[4:5]
	s_add_i32 s4, s10, 5
	s_min_u32 s5, s4, 0x10a
	s_lshl_b32 s5, s5, 4
	s_cmp_lt_u32 s4, 11
	s_movk_i32 s4, 0xff50
	s_movk_i32 s11, 0xaf
	s_cselect_b32 s4, 0x50, s4
	s_cselect_b32 s11, s11, 0x10af
	s_cselect_b32 s12, s8, s2
	s_add_i32 s13, s5, s4
	s_sub_i32 s11, s11, s5
	s_and_b64 s[4:5], s[6:7], exec
	s_cselect_b32 s4, s13, s11
	s_add_i32 s4, s4, s12
	v_add_u32_e32 v56, s4, v178
	v_max_i32_e32 v56, 0, v56
	v_mad_u32_u24 v56, v56, s63, v82
	v_ashrrev_i32_e32 v57, 31, v56
	v_lshl_add_u64 v[56:57], v[56:57], 1, s[82:83]
	global_load_dwordx4 v[56:59], v[56:57], off
	ds_read_b128 v[92:95], v83 offset:5120
	ds_read_b128 v[96:99], v83 offset:5136
	ds_read_b128 v[100:103], v83
	ds_read_b128 v[104:107], v83 offset:16
	ds_read_b128 v[108:111], v83 offset:32
	ds_read_b128 v[112:115], v83 offset:48
	ds_read_b128 v[116:119], v83 offset:5152
	ds_read_b128 v[120:123], v83 offset:5168
	s_waitcnt lgkmcnt(7)
	v_fma_f32 v92, v71, v89, v92
	s_waitcnt lgkmcnt(5)
	v_fma_f32 v91, v75, v90, v100
	s_waitcnt lgkmcnt(0)
	v_fma_f32 v89, v70, v89, v91
	v_fma_f32 v90, v70, v90, v92
	v_fma_f32 v92, v75, v90, v101
	v_fma_f32 v93, v71, v89, v93
	v_cvt_pk_bf16_f32 v91, v89, v90
	v_fma_f32 v92, v70, v89, v92
	v_fma_f32 v90, v70, v90, v93
	v_add_u32_e32 v89, 0x5000, v87
	v_cvt_pk_bf16_f32 v93, v92, v90
	ds_write2_b32 v89, v91, v93 offset1:68
	v_fma_f32 v91, v75, v90, v102
	v_fma_f32 v93, v71, v92, v94
	v_fma_f32 v91, v70, v92, v91
	v_fma_f32 v90, v70, v90, v93
	v_fma_f32 v93, v75, v90, v103
	v_cvt_pk_bf16_f32 v92, v91, v90
	v_fma_f32 v94, v71, v91, v95
	v_fma_f32 v91, v70, v91, v93
	v_fma_f32 v90, v70, v90, v94
	v_cvt_pk_bf16_f32 v93, v91, v90
	ds_write2_b32 v89, v92, v93 offset0:136 offset1:204
	v_fma_f32 v93, v71, v91, v96
	s_waitcnt lgkmcnt(6)
	v_fma_f32 v92, v75, v90, v104
	v_fma_f32 v91, v70, v91, v92
	v_fma_f32 v90, v70, v90, v93
	v_fma_f32 v93, v75, v90, v105
	v_fma_f32 v94, v71, v91, v97
	v_cvt_pk_bf16_f32 v92, v91, v90
	v_fma_f32 v91, v70, v91, v93
	v_fma_f32 v93, v70, v90, v94
	v_add_u32_e32 v90, 0x5400, v87
	v_cvt_pk_bf16_f32 v94, v91, v93
	ds_write2_b32 v90, v92, v94 offset0:16 offset1:84
	v_fma_f32 v92, v75, v93, v106
	v_fma_f32 v94, v71, v91, v98
	v_fma_f32 v91, v70, v91, v92
	v_fma_f32 v92, v70, v93, v94
	v_fma_f32 v94, v75, v92, v107
	v_cvt_pk_bf16_f32 v93, v91, v92
	v_fma_f32 v95, v71, v91, v99
	v_fma_f32 v91, v70, v91, v94
	v_fma_f32 v92, v70, v92, v95
	v_cvt_pk_bf16_f32 v94, v91, v92
	ds_write2_b32 v90, v93, v94 offset0:152 offset1:220
	s_waitcnt lgkmcnt(5)
	v_fma_f32 v94, v71, v91, v116
	v_fma_f32 v93, v75, v92, v108
	v_fma_f32 v91, v70, v91, v93
	v_fma_f32 v92, v70, v92, v94
	v_fma_f32 v94, v75, v92, v109
	v_fma_f32 v95, v71, v91, v117
	v_cvt_pk_bf16_f32 v93, v91, v92
	v_fma_f32 v91, v70, v91, v94
	v_fma_f32 v94, v70, v92, v95
	v_add_u32_e32 v92, 0x5800, v87
	v_cvt_pk_bf16_f32 v95, v91, v94
	ds_write2_b32 v92, v93, v95 offset0:32 offset1:100
	v_fma_f32 v93, v75, v94, v110
	v_fma_f32 v95, v71, v91, v118
	v_fma_f32 v91, v70, v91, v93
	v_fma_f32 v93, v70, v94, v95
	v_fma_f32 v95, v75, v93, v111
	v_cvt_pk_bf16_f32 v94, v91, v93
	v_fma_f32 v96, v71, v91, v119
	v_fma_f32 v91, v70, v91, v95
	v_fma_f32 v93, v70, v93, v96
	v_cvt_pk_bf16_f32 v95, v91, v93
	ds_write2_b32 v92, v94, v95 offset0:168 offset1:236
	s_waitcnt lgkmcnt(6)
	v_fma_f32 v95, v71, v91, v120
	v_fma_f32 v94, v75, v93, v112
	v_fma_f32 v91, v70, v91, v94
	v_fma_f32 v93, v70, v93, v95
	v_fma_f32 v95, v75, v93, v113
	v_fma_f32 v96, v71, v91, v121
	v_cvt_pk_bf16_f32 v94, v91, v93
	v_fma_f32 v95, v70, v91, v95
	v_fma_f32 v93, v70, v93, v96
	v_add_u32_e32 v91, 0x5c00, v87
	v_cvt_pk_bf16_f32 v96, v95, v93
	ds_write2_b32 v91, v94, v96 offset0:48 offset1:116
	v_fma_f32 v94, v75, v93, v114
	v_fma_f32 v96, v71, v95, v122
	v_fma_f32 v94, v70, v95, v94
	v_fma_f32 v93, v70, v93, v96
	v_fma_f32 v96, v75, v93, v115
	v_cvt_pk_bf16_f32 v95, v94, v93
	v_fma_f32 v97, v71, v94, v123
	v_fma_f32 v94, v70, v94, v96
	v_fma_f32 v93, v70, v93, v97
	v_cvt_pk_bf16_f32 v96, v94, v93
	ds_write2_b32 v91, v95, v96 offset0:184 offset1:252
	s_waitcnt lgkmcnt(0)
	s_barrier
	s_and_saveexec_b64 s[4:5], vcc
	v_add_u32_e32 v95, v84, v85
	s_waitcnt vmcnt(3)
	ds_write_b128 v95, v[64:67] offset:29696
	s_or_b64 exec, exec, s[4:5]
	s_add_i32 s4, s10, 6
	s_min_u32 s5, s4, 0x10a
	s_lshl_b32 s5, s5, 4
	s_cmp_lt_u32 s4, 11
	s_movk_i32 s4, 0xff50
	s_movk_i32 s11, 0xaf
	s_cselect_b32 s4, 0x50, s4
	s_cselect_b32 s11, s11, 0x10af
	s_cselect_b32 s12, s8, s2
	s_add_i32 s13, s5, s4
	s_sub_i32 s11, s11, s5
	s_and_b64 s[4:5], s[6:7], exec
	s_cselect_b32 s4, s13, s11
	s_add_i32 s4, s4, s12
	v_add_u32_e32 v64, s4, v178
	v_max_i32_e32 v64, 0, v64
	v_mad_u32_u24 v64, v64, s63, v82
	v_ashrrev_i32_e32 v65, 31, v64
	v_lshl_add_u64 v[64:65], v[64:65], 1, s[82:83]
	global_load_dwordx4 v[64:67], v[64:65], off
	ds_read_b128 v[96:99], v83 offset:15360
	ds_read_b128 v[100:103], v83 offset:15376
	ds_read_b128 v[104:107], v83 offset:10240
	ds_read_b128 v[108:111], v83 offset:10256
	ds_read_b128 v[112:115], v83 offset:10272
	ds_read_b128 v[116:119], v83 offset:10288
	ds_read_b128 v[120:123], v83 offset:15392
	ds_read_b128 v[124:127], v83 offset:15408
	s_waitcnt lgkmcnt(7)
	v_fma_f32 v96, v71, v94, v96
	s_waitcnt lgkmcnt(5)
	v_fma_f32 v95, v75, v93, v104
	s_waitcnt lgkmcnt(0)
	s_add_i32 s10, s10, 7
	v_fma_f32 v94, v70, v94, v95
	v_fma_f32 v93, v70, v93, v96
	s_cmpk_gt_u32 s10, 0x10e
	v_fma_f32 v96, v75, v93, v105
	v_cvt_pk_bf16_f32 v95, v94, v93
	v_fma_f32 v97, v71, v94, v97
	v_fma_f32 v94, v70, v94, v96
	v_fma_f32 v93, v70, v93, v97
	v_cvt_pk_bf16_f32 v96, v94, v93
	ds_write2_b32 v88, v95, v96 offset0:64 offset1:132
	v_fma_f32 v96, v71, v94, v98
	v_fma_f32 v95, v75, v93, v106
	v_fma_f32 v94, v70, v94, v95
	v_fma_f32 v93, v70, v93, v96
	v_fma_f32 v96, v75, v93, v107
	v_cvt_pk_bf16_f32 v95, v94, v93
	v_fma_f32 v97, v71, v94, v99
	v_fma_f32 v94, v70, v94, v96
	v_fma_f32 v93, v70, v93, v97
	v_cvt_pk_bf16_f32 v96, v94, v93
	ds_write2_b32 v86, v95, v96 offset0:72 offset1:140
	v_fma_f32 v96, v71, v94, v100
	s_waitcnt lgkmcnt(6)
	v_fma_f32 v95, v75, v93, v108
	v_fma_f32 v94, v70, v94, v95
	v_fma_f32 v93, v70, v93, v96
	v_fma_f32 v96, v75, v93, v109
	v_cvt_pk_bf16_f32 v95, v94, v93
	v_fma_f32 v97, v71, v94, v101
	v_fma_f32 v94, v70, v94, v96
	v_fma_f32 v93, v70, v93, v97
	v_cvt_pk_bf16_f32 v96, v94, v93
	ds_write2_b32 v81, v95, v96 offset0:80 offset1:148
	v_fma_f32 v96, v71, v94, v102
	v_fma_f32 v95, v75, v93, v110
	v_fma_f32 v94, v70, v94, v95
	v_fma_f32 v93, v70, v93, v96
	v_fma_f32 v96, v75, v93, v111
	v_cvt_pk_bf16_f32 v95, v94, v93
	v_fma_f32 v97, v71, v94, v103
	v_fma_f32 v94, v70, v94, v96
	v_fma_f32 v93, v70, v93, v97
	v_cvt_pk_bf16_f32 v96, v94, v93
	ds_write2_b32 v80, v95, v96 offset0:88 offset1:156
	s_waitcnt lgkmcnt(5)
	v_fma_f32 v96, v71, v94, v120
	v_fma_f32 v95, v75, v93, v112
	v_fma_f32 v94, v70, v94, v95
	v_fma_f32 v93, v70, v93, v96
	v_fma_f32 v96, v75, v93, v113
	v_cvt_pk_bf16_f32 v95, v94, v93
	v_fma_f32 v97, v71, v94, v121
	v_fma_f32 v94, v70, v94, v96
	v_fma_f32 v93, v70, v93, v97
	v_cvt_pk_bf16_f32 v96, v94, v93
	ds_write2_b32 v79, v95, v96 offset0:96 offset1:164
	v_fma_f32 v96, v71, v94, v122
	v_fma_f32 v95, v75, v93, v114
	v_fma_f32 v94, v70, v94, v95
	v_fma_f32 v93, v70, v93, v96
	v_fma_f32 v96, v75, v93, v115
	v_cvt_pk_bf16_f32 v95, v94, v93
	v_fma_f32 v97, v71, v94, v123
	v_fma_f32 v94, v70, v94, v96
	v_fma_f32 v93, v70, v93, v97
	v_cvt_pk_bf16_f32 v96, v94, v93
	ds_write2_b32 v78, v95, v96 offset0:104 offset1:172
	s_waitcnt lgkmcnt(6)
	v_fma_f32 v96, v71, v94, v124
	v_fma_f32 v95, v75, v93, v116
	v_fma_f32 v94, v70, v94, v95
	v_fma_f32 v93, v70, v93, v96
	v_fma_f32 v96, v75, v93, v117
	v_cvt_pk_bf16_f32 v95, v94, v93
	v_fma_f32 v97, v71, v94, v125
	v_fma_f32 v94, v70, v94, v96
	v_fma_f32 v93, v70, v93, v97
	v_cvt_pk_bf16_f32 v96, v94, v93
	ds_write2_b32 v77, v95, v96 offset0:112 offset1:180
	v_fma_f32 v96, v71, v94, v126
	v_fma_f32 v95, v75, v93, v118
	v_fma_f32 v94, v70, v94, v95
	v_fma_f32 v93, v70, v93, v96
	v_fma_f32 v96, v75, v93, v119
	v_cvt_pk_bf16_f32 v95, v94, v93
	v_fma_f32 v97, v71, v94, v127
	v_fma_f32 v94, v70, v94, v96
	v_fma_f32 v93, v70, v93, v97
	v_cvt_pk_bf16_f32 v96, v94, v93
	ds_write2_b32 v76, v95, v96 offset0:120 offset1:188
	s_waitcnt lgkmcnt(0)
	s_barrier
	s_cbranch_scc1 .LBB0_373
	s_and_saveexec_b64 s[4:5], vcc
	s_cbranch_execz .LBB0_372
	v_add_u32_e32 v95, v84, v85
	s_waitcnt vmcnt(3)
	ds_write_b128 v95, v[60:63] offset:29184
	s_branch .LBB0_372

.LBB0_425:
	s_or_b64 exec, exec, s[4:5]
	s_add_i32 s4, s37, s33
	s_or_b32 s0, s35, s0
	v_add_u32_e32 v52, s4, v180
	v_mov_b32_e32 v53, v181
	s_movk_i32 s33, 0xf7f
	s_mov_b32 s42, 64
	s_mov_b32 s43, 5
	s_movk_i32 s44, 0x42
	s_waitcnt vmcnt(0)
	s_branch .LBB0_428

.LBB0_428:
	s_and_saveexec_b64 s[4:5], s[6:7]
	s_cbranch_execz .LBB0_430
	s_waitcnt vmcnt(14)
	ds_write2st64_b32 v60, v55, v58 offset1:1
	s_cmp_gt_u32 s43, 0x43
	s_cbranch_scc1 .Lgdn_nogA
	s_add_i32 s73, s33, 64
	s_and_b64 s[70:71], s[26:27], exec
	s_cselect_b32 s74, s43, s44
	s_cselect_b32 s73, s42, s73
	s_lshl_b32 s74, s74, 6
	s_add_i32 s74, s74, s2
	s_add_i32 s73, s73, s1
	v_add_u32_e32 v44, s74, v68
	v_lshl_add_u32 v180, v44, 4, v59
	v_lshl_add_u64 v[44:45], v[180:181], 2, s[86:87]
	global_load_dword v55, v[44:45], off
	v_add_u32_e32 v44, s73, v54
	v_lshl_add_u32 v180, v44, 4, v89
	v_lshl_add_u64 v[44:45], v[180:181], 2, s[86:87]
	global_load_dword v58, v[44:45], off
.Lgdn_nogA:
.LBB0_430:
	s_or_b64 exec, exec, s[4:5]
	ds_read_b128 v[44:47], v62 offset:18432
	ds_read_b128 v[48:51], v64
	ds_read_b128 v[106:109], v62 offset:18496
	ds_read_b128 v[110:113], v61
	ds_read_b128 v[114:117], v65
	ds_read_b64_tr_b16 v[122:123], v67 offset:46080
	ds_read_b128 v[118:121], v64 offset:64
	s_and_b64 vcc, exec, s[24:25]
	s_waitcnt lgkmcnt(5)
	v_mfma_f32_16x16x32_bf16 v[48:51], v[44:47], v[48:51], 0
	s_waitcnt lgkmcnt(1)
	v_lshlrev_b32_e32 v126, 16, v122
	v_and_b32_e32 v127, 0xffff0000, v122
	v_mfma_f32_16x16x32_bf16 v[44:47], v[44:47], v[114:117], 0
	ds_read_b128 v[114:117], v65 offset:64
	ds_read_b64_tr_b16 v[124:125], v69 offset:46080
	s_waitcnt lgkmcnt(2)
	v_mfma_f32_16x16x32_bf16 v[48:51], v[106:109], v[118:121], v[48:51]
	v_lshlrev_b32_e32 v118, 16, v123
	v_and_b32_e32 v119, 0xffff0000, v123
	s_waitcnt lgkmcnt(1)
	v_mfma_f32_16x16x32_bf16 v[44:47], v[106:109], v[114:117], v[44:47]
	s_nop 3
	v_add_f32_e64 v48, v126, -v48
	v_add_f32_e64 v49, v127, -v49
	v_pk_add_f32 v[50:51], v[118:119], v[50:51] neg_lo:[0,1] neg_hi:[0,1]
	v_pk_mul_f32 v[48:49], v[110:111], v[48:49]
	v_pk_mul_f32 v[50:51], v[112:113], v[50:51]
	v_cvt_pk_bf16_f32 v48, v48, v49
	v_cvt_pk_bf16_f32 v49, v50, v51
	ds_write_b64 v70, v[48:49] offset:55296
	s_waitcnt lgkmcnt(1)
	v_lshlrev_b32_e32 v48, 16, v124
	v_and_b32_e32 v49, 0xffff0000, v124
	v_pk_add_f32 v[44:45], v[48:49], v[44:45] neg_lo:[0,1] neg_hi:[0,1]
	v_lshlrev_b32_e32 v48, 16, v125
	v_and_b32_e32 v49, 0xffff0000, v125
	v_pk_add_f32 v[46:47], v[48:49], v[46:47] neg_lo:[0,1] neg_hi:[0,1]
	v_pk_mul_f32 v[44:45], v[110:111], v[44:45]
	v_pk_mul_f32 v[46:47], v[112:113], v[46:47]
	v_cvt_pk_bf16_f32 v44, v44, v45
	v_cvt_pk_bf16_f32 v45, v46, v47
	ds_write_b64 v71, v[44:45] offset:55296
	ds_read_b128 v[44:47], v72
	ds_read_b128 v[48:51], v73
	ds_read_b32 v105, v63
	ds_read_b128 v[106:109], v66
	ds_read_b128 v[110:113], v72 offset:64
	ds_read_b128 v[114:117], v73 offset:64
	s_waitcnt lgkmcnt(4)
	v_mfma_f32_16x16x32_bf16 v[44:47], v[44:47], v[48:51], 0
	s_waitcnt lgkmcnt(2)
	v_sub_f32_e32 v48, v105, v106
	v_sub_f32_e32 v49, v105, v107
	v_mul_f32_e32 v48, 0x3fb8aa3b, v48
	v_mul_f32_e32 v49, 0x3fb8aa3b, v49
	v_exp_f32_e32 v48, v48
	v_exp_f32_e32 v49, v49
	s_waitcnt lgkmcnt(0)
	v_mfma_f32_16x16x32_bf16 v[44:47], v[110:113], v[114:117], v[44:47]
	s_nop 7
	v_mul_f32_e32 v44, v44, v48
	v_mul_f32_e32 v45, v45, v49
	v_sub_f32_e32 v48, v105, v108
	v_sub_f32_e32 v49, v105, v109
	v_mul_f32_e32 v48, 0x3fb8aa3b, v48
	v_mul_f32_e32 v49, 0x3fb8aa3b, v49
	v_exp_f32_e32 v48, v48
	v_exp_f32_e32 v49, v49
	v_cndmask_b32_e64 v44, v44, 0, s[8:9]
	v_cndmask_b32_e64 v45, 0, v45, s[10:11]
	v_mul_f32_e32 v46, v46, v48
	v_mul_f32_e32 v47, v47, v49
	v_cndmask_b32_e64 v46, v46, 0, s[12:13]
	v_cndmask_b32_e64 v47, v47, 0, s[14:15]
	v_cvt_pk_bf16_f32 v44, v44, v45
	v_cvt_pk_bf16_f32 v45, v46, v47
	ds_write_b64 v74, v[44:45] offset:9216
	s_waitcnt lgkmcnt(0)
	s_barrier
	ds_read_b128 v[44:47], v62
	ds_read_b128 v[48:51], v77 offset:55296
	ds_read_b128 v[106:109], v62 offset:64
	ds_read_b128 v[110:113], v77 offset:55360
	ds_read_b128 v[114:117], v78 offset:55296
	ds_read_b128 v[118:121], v78 offset:55360
	s_waitcnt lgkmcnt(4)
	v_mfma_f32_16x16x32_bf16 v[48:51], v[44:47], v[48:51], 0
	s_waitcnt lgkmcnt(1)
	v_mfma_f32_16x16x32_bf16 v[44:47], v[44:47], v[114:117], 0
	v_mfma_f32_16x16x32_bf16 v[48:51], v[106:109], v[110:113], v[48:51]
	s_waitcnt lgkmcnt(0)
	v_mfma_f32_16x16x32_bf16 v[44:47], v[106:109], v[118:121], v[44:47]
	s_nop 5
	v_cvt_pk_bf16_f32 v48, v48, v49
	v_cvt_pk_bf16_f32 v49, v50, v51
	v_cvt_pk_bf16_f32 v44, v44, v45
	v_cvt_pk_bf16_f32 v45, v46, v47
	ds_write_b64 v79, v[48:49] offset:64512
	ds_write_b64 v71, v[44:45] offset:64512
	s_cbranch_vccnz .LBB0_432
	ds_read_b128 v[44:47], v80
	ds_read_b128 v[48:51], v80 offset:64
	ds_read_b128 v[106:109], v81
	ds_read_b128 v[110:113], v81 offset:64
	s_waitcnt lgkmcnt(1)
	v_mfma_f32_16x16x32_bf16 v[44:47], v[44:47], v[106:109], 0
	s_waitcnt lgkmcnt(0)
	v_mfma_f32_16x16x32_bf16 v[44:47], v[48:51], v[110:113], v[44:47]
	ds_read_b32 v105, v75
	ds_read_b128 v[48:51], v76
	s_waitcnt lgkmcnt(0)
	v_sub_f32_e32 v48, v105, v48
	v_mul_f32_e32 v48, 0x3fb8aa3b, v48
	v_exp_f32_e32 v48, v48
	s_nop 1
	v_mul_f32_e32 v44, v44, v48
	v_sub_f32_e32 v48, v105, v49
	v_mul_f32_e32 v48, 0x3fb8aa3b, v48
	v_exp_f32_e32 v48, v48
	v_cndmask_b32_e64 v44, v44, 0, s[16:17]
	v_mul_f32_e32 v45, v45, v48
	v_sub_f32_e32 v48, v105, v50
	v_mul_f32_e32 v48, 0x3fb8aa3b, v48
	v_exp_f32_e32 v48, v48
	v_cndmask_b32_e64 v45, 0, v45, s[18:19]
	v_cvt_pk_bf16_f32 v44, v44, v45
	v_mul_f32_e32 v46, v46, v48
	v_sub_f32_e32 v48, v105, v51
	v_mul_f32_e32 v48, 0x3fb8aa3b, v48
	v_exp_f32_e32 v48, v48
	v_cndmask_b32_e64 v46, v46, 0, s[20:21]
	v_mul_f32_e32 v47, v47, v48
	v_cndmask_b32_e64 v47, v47, 0, s[22:23]
	v_cvt_pk_bf16_f32 v45, v46, v47
	ds_write_b64 v82, v[44:45] offset:9216

.LBB0_436:
	v_add_u32_e32 v105, s34, v85
	v_cvt_pk_bf16_f32 v48, v48, v49
	v_cvt_pk_bf16_f32 v49, v50, v51
	v_lshl_or_b32 v50, v105, 10, v52
	v_mov_b32_e32 v51, v53
	v_lshl_add_u64 v[50:51], v[50:51], 1, s[28:29]
	global_store_dwordx2 v[50:51], v[48:49], off offset:1024
	v_add_u32_e32 v48, s34, v86
	v_cvt_pk_bf16_f32 v44, v44, v45
	v_cvt_pk_bf16_f32 v45, v46, v47
	v_lshl_or_b32 v46, v48, 10, v52
	v_mov_b32_e32 v47, v53
	v_lshl_add_u64 v[46:47], v[46:47], 1, s[28:29]
	global_store_dwordx2 v[46:47], v[44:45], off offset:1024
	v_mov_b32_e32 v44, v68
	s_waitcnt vmcnt(8)
	v_lshlrev_b32_e32 v108, 16, v12
	v_ashrrev_i32_e32 v45, 3, v44
	v_lshlrev_b32_e32 v44, 4, v44
	v_mul_lo_u32 v105, v45, s61
	v_and_b32_e32 v116, 0x70, v44
	v_add3_u32 v117, 0, v105, v116
	v_lshl_add_u32 v44, v45, 2, 0
	ds_write_b128 v117, v[4:7]
	v_add_u32_e32 v44, 0x1fa00, v44
	ds_read_b32 v118, v44
	v_and_b32_e32 v109, 0xffff0000, v12
	v_and_b32_e32 v45, 0xffff0000, v8
	v_lshlrev_b32_e32 v110, 16, v13
	v_and_b32_e32 v111, 0xffff0000, v13
	s_waitcnt lgkmcnt(0)
	v_mul_f32_e32 v44, 0x3fb8aa3b, v118
	v_exp_f32_e32 v106, v44
	v_lshlrev_b32_e32 v44, 16, v8
	v_lshlrev_b32_e32 v114, 16, v11
	v_and_b32_e32 v115, 0xffff0000, v11
	v_pk_mul_f32 v[46:47], v[106:107], v[108:109] op_sel_hi:[0,1]
	v_cvt_pk_bf16_f32 v48, v46, v47
	v_lshlrev_b32_e32 v46, 16, v9
	v_and_b32_e32 v47, 0xffff0000, v9
	v_pk_mul_f32 v[44:45], v[106:107], v[44:45] op_sel_hi:[0,1]
	v_pk_mul_f32 v[46:47], v[106:107], v[46:47] op_sel_hi:[0,1]
	v_cvt_pk_bf16_f32 v44, v44, v45
	v_cvt_pk_bf16_f32 v45, v46, v47
	v_pk_mul_f32 v[46:47], v[106:107], v[110:111] op_sel_hi:[0,1]
	v_cvt_pk_bf16_f32 v49, v46, v47
	v_lshlrev_b32_e32 v46, 16, v10
	v_and_b32_e32 v47, 0xffff0000, v10
	v_pk_mul_f32 v[46:47], v[106:107], v[46:47] op_sel_hi:[0,1]
	v_pk_mul_f32 v[114:115], v[106:107], v[114:115] op_sel_hi:[0,1]
	v_cvt_pk_bf16_f32 v46, v46, v47
	v_lshlrev_b32_e32 v112, 16, v14
	v_and_b32_e32 v113, 0xffff0000, v14
	v_cvt_pk_bf16_f32 v47, v114, v115
	v_lshlrev_b32_e32 v114, 16, v15
	v_and_b32_e32 v115, 0xffff0000, v15
	v_pk_mul_f32 v[50:51], v[106:107], v[112:113] op_sel_hi:[0,1]
	v_pk_mul_f32 v[106:107], v[106:107], v[114:115] op_sel_hi:[0,1]
	v_readlane_b32 s4, v255, 4
	v_cvt_pk_bf16_f32 v50, v50, v51
	v_cvt_pk_bf16_f32 v51, v106, v107
	v_add3_u32 v106, s4, v105, v116
	ds_write_b128 v106, v[44:47]
	ds_write_b128 v117, v[48:51] offset:18432
	v_add3_u32 v44, s40, v105, v116
	ds_write_b128 v44, v[8:11]
	v_add3_u32 v44, s41, v105, v116
	ds_write_b128 v44, v[12:15]
	s_waitcnt vmcnt(8)
	ds_write_b128 v117, v[16:19] offset:46080
	v_mov_b32_e32 v44, s72
	ds_read_b32 v44, v44
	v_readlane_b32 s4, v255, 6
	s_cmp_gt_u32 s45, 64
	s_waitcnt lgkmcnt(0)
	v_sub_f32_e32 v44, v44, v118
	v_mul_f32_e32 v44, 0x3fb8aa3b, v44
	v_exp_f32_e32 v48, v44
	s_nop 0
	v_pk_mul_f32 v[44:45], v[48:49], v[108:109] op_sel_hi:[0,1]
	v_pk_mul_f32 v[46:47], v[48:49], v[110:111] op_sel_hi:[0,1]
	v_cvt_pk_bf16_f32 v44, v44, v45
	v_cvt_pk_bf16_f32 v45, v46, v47
	v_pk_mul_f32 v[46:47], v[48:49], v[112:113] op_sel_hi:[0,1]
	v_pk_mul_f32 v[48:49], v[48:49], v[114:115] op_sel_hi:[0,1]
	v_cvt_pk_bf16_f32 v46, v46, v47
	v_cvt_pk_bf16_f32 v47, v48, v49
	v_add3_u32 v48, s4, v105, v116
	ds_write_b128 v48, v[44:47]
	s_waitcnt lgkmcnt(0)
	s_barrier
	s_cbranch_scc1 .Lgdn_skipA
	s_and_b64 s[4:5], s[26:27], exec
	s_cselect_b32 s4, s43, s44
	s_lshl_b32 s35, s4, 6
	s_add_i32 s35, s35, s2
	s_add_i32 s34, s33, 64
	v_mov_b32_e32 v4, v68
	s_and_b64 s[4:5], s[26:27], exec
	s_cselect_b32 s34, s42, s34
	v_ashrrev_i32_e32 v6, 3, v4
	s_add_i32 s34, s34, s1
	v_add_u32_e32 v5, s35, v6
	v_lshlrev_b32_e32 v4, 3, v4
	v_mul_lo_u32 v6, v6, s39
	v_and_b32_e32 v7, 56, v4
	v_add_u32_e32 v6, s34, v6
	v_or_b32_e32 v4, s0, v7
	v_mul_u32_u24_e32 v6, 0x300, v6
	v_mad_u32_u24 v4, v5, s63, v4
	v_or3_b32 v6, v6, s37, v7
	v_ashrrev_i32_e32 v5, 31, v4
	v_ashrrev_i32_e32 v7, 31, v6
	v_lshl_add_u64 v[4:5], v[4:5], 1, s[82:83]
	v_lshl_add_u64 v[16:17], v[6:7], 1, s[84:85]
	global_load_dwordx4 v[4:7], v[4:5], off
	s_nop 0
	global_load_dwordx4 v[8:11], v[16:17], off
	global_load_dwordx4 v[12:15], v[16:17], off offset:512
	s_nop 0
	global_load_dwordx4 v[16:19], v[16:17], off offset:1024
	s_and_saveexec_b64 s[4:5], s[6:7]
	s_cbranch_execz .LBB0_439

.LBB0_440:
	s_add_i32 s48, s45, 1
	s_cmpk_lt_u32 s48, 0x43
	s_cselect_b64 s[34:35], -1, 0
	s_and_b64 s[50:51], s[6:7], s[34:35]
	s_and_saveexec_b64 s[4:5], s[50:51]
	s_cbranch_execz .LBB0_442
	s_waitcnt vmcnt(14)
	ds_write2st64_b32 v90, v56, v57 offset1:1
	s_cmp_gt_u32 s48, 64
	s_cbranch_scc1 .Lgdn_nogB
	s_add_i32 s74, s43, 1
	s_add_i32 s73, s44, -1
	s_and_b64 s[70:71], s[26:27], exec
	s_cselect_b32 s74, s74, s73
	s_cselect_b32 s73, s47, s33
	s_lshl_b32 s74, s74, 6
	s_add_i32 s74, s74, s2
	s_add_i32 s73, s73, s1
	v_add_u32_e32 v44, s74, v68
	v_lshl_add_u32 v180, v44, 4, v59
	v_lshl_add_u64 v[44:45], v[180:181], 2, s[86:87]
	global_load_dword v56, v[44:45], off
	v_add_u32_e32 v44, s73, v54
	v_lshl_add_u32 v180, v44, 4, v89
	v_lshl_add_u64 v[44:45], v[180:181], 2, s[86:87]
	global_load_dword v57, v[44:45], off
.Lgdn_nogB:
.LBB0_442:
	s_or_b64 exec, exec, s[4:5]
	ds_read_b128 v[44:47], v62 offset:18432
	ds_read_b128 v[48:51], v91
	ds_read_b64_tr_b16 v[122:123], v69 offset:46080
	ds_read_b128 v[106:109], v92
	ds_read_b128 v[110:113], v93
	ds_read_b128 v[114:117], v62 offset:18496
	ds_read_b128 v[118:121], v91 offset:64
	s_and_b64 vcc, exec, s[24:25]
	s_waitcnt lgkmcnt(5)
	v_mfma_f32_16x16x32_bf16 v[48:51], v[44:47], v[48:51], 0
	s_waitcnt lgkmcnt(2)
	v_mfma_f32_16x16x32_bf16 v[44:47], v[44:47], v[110:113], 0
	ds_read_b64_tr_b16 v[124:125], v67 offset:46080
	ds_read_b128 v[110:113], v93 offset:64
	s_waitcnt lgkmcnt(1)
	v_lshlrev_b32_e32 v126, 16, v124
	v_mfma_f32_16x16x32_bf16 v[48:51], v[114:117], v[118:121], v[48:51]
	v_and_b32_e32 v127, 0xffff0000, v124
	v_lshlrev_b32_e32 v118, 16, v125
	v_and_b32_e32 v119, 0xffff0000, v125
	s_waitcnt lgkmcnt(0)
	v_mfma_f32_16x16x32_bf16 v[44:47], v[114:117], v[110:113], v[44:47]
	s_nop 2
	v_add_f32_e64 v48, v126, -v48
	v_add_f32_e64 v49, v127, -v49
	v_pk_add_f32 v[50:51], v[118:119], v[50:51] neg_lo:[0,1] neg_hi:[0,1]
	v_pk_mul_f32 v[48:49], v[106:107], v[48:49]
	v_pk_mul_f32 v[50:51], v[108:109], v[50:51]
	v_cvt_pk_bf16_f32 v48, v48, v49
	v_cvt_pk_bf16_f32 v49, v50, v51
	ds_write_b64 v70, v[48:49] offset:55296
	v_lshlrev_b32_e32 v48, 16, v122
	v_and_b32_e32 v49, 0xffff0000, v122
	v_pk_add_f32 v[44:45], v[48:49], v[44:45] neg_lo:[0,1] neg_hi:[0,1]
	v_lshlrev_b32_e32 v48, 16, v123
	v_and_b32_e32 v49, 0xffff0000, v123
	v_pk_add_f32 v[46:47], v[48:49], v[46:47] neg_lo:[0,1] neg_hi:[0,1]
	v_pk_mul_f32 v[44:45], v[106:107], v[44:45]
	v_pk_mul_f32 v[46:47], v[108:109], v[46:47]
	v_cvt_pk_bf16_f32 v44, v44, v45
	v_cvt_pk_bf16_f32 v45, v46, v47
	ds_write_b64 v71, v[44:45] offset:55296
	ds_read_b128 v[44:47], v72
	ds_read_b128 v[48:51], v73
	ds_read_b32 v105, v94
	ds_read_b128 v[106:109], v95
	ds_read_b128 v[110:113], v72 offset:64
	ds_read_b128 v[114:117], v73 offset:64
	s_waitcnt lgkmcnt(4)
	v_mfma_f32_16x16x32_bf16 v[44:47], v[44:47], v[48:51], 0
	s_waitcnt lgkmcnt(2)
	v_sub_f32_e32 v48, v105, v106
	v_sub_f32_e32 v49, v105, v107
	v_mul_f32_e32 v48, 0x3fb8aa3b, v48
	v_mul_f32_e32 v49, 0x3fb8aa3b, v49
	v_exp_f32_e32 v48, v48
	v_exp_f32_e32 v49, v49
	s_waitcnt lgkmcnt(0)
	v_mfma_f32_16x16x32_bf16 v[44:47], v[110:113], v[114:117], v[44:47]
	s_nop 7
	v_mul_f32_e32 v44, v44, v48
	v_mul_f32_e32 v45, v45, v49
	v_sub_f32_e32 v48, v105, v108
	v_sub_f32_e32 v49, v105, v109
	v_mul_f32_e32 v48, 0x3fb8aa3b, v48
	v_mul_f32_e32 v49, 0x3fb8aa3b, v49
	v_exp_f32_e32 v48, v48
	v_exp_f32_e32 v49, v49
	v_cndmask_b32_e64 v44, v44, 0, s[8:9]
	v_cndmask_b32_e64 v45, 0, v45, s[10:11]
	v_mul_f32_e32 v46, v46, v48
	v_mul_f32_e32 v47, v47, v49
	v_cndmask_b32_e64 v46, v46, 0, s[12:13]
	v_cndmask_b32_e64 v47, v47, 0, s[14:15]
	v_cvt_pk_bf16_f32 v44, v44, v45
	v_cvt_pk_bf16_f32 v45, v46, v47
	ds_write_b64 v74, v[44:45] offset:9216
	s_waitcnt lgkmcnt(0)
	s_barrier
	ds_read_b128 v[44:47], v62
	ds_read_b128 v[48:51], v77 offset:55296
	ds_read_b128 v[106:109], v62 offset:64
	ds_read_b128 v[110:113], v77 offset:55360
	ds_read_b128 v[114:117], v78 offset:55296
	ds_read_b128 v[118:121], v78 offset:55360
	s_waitcnt lgkmcnt(4)
	v_mfma_f32_16x16x32_bf16 v[48:51], v[44:47], v[48:51], 0
	s_waitcnt lgkmcnt(1)
	v_mfma_f32_16x16x32_bf16 v[44:47], v[44:47], v[114:117], 0
	v_mfma_f32_16x16x32_bf16 v[48:51], v[106:109], v[110:113], v[48:51]
	s_waitcnt lgkmcnt(0)
	v_mfma_f32_16x16x32_bf16 v[44:47], v[106:109], v[118:121], v[44:47]
	s_nop 5
	v_cvt_pk_bf16_f32 v48, v48, v49
	v_cvt_pk_bf16_f32 v49, v50, v51
	v_cvt_pk_bf16_f32 v44, v44, v45
	v_cvt_pk_bf16_f32 v45, v46, v47
	ds_write_b64 v79, v[48:49] offset:64512
	ds_write_b64 v71, v[44:45] offset:64512
	s_cbranch_vccnz .LBB0_444
	ds_read_b128 v[44:47], v80
	ds_read_b128 v[48:51], v80 offset:64
	ds_read_b128 v[106:109], v81
	ds_read_b128 v[110:113], v81 offset:64
	s_waitcnt lgkmcnt(1)
	v_mfma_f32_16x16x32_bf16 v[44:47], v[44:47], v[106:109], 0
	s_waitcnt lgkmcnt(0)
	v_mfma_f32_16x16x32_bf16 v[44:47], v[48:51], v[110:113], v[44:47]
	ds_read_b32 v105, v96
	ds_read_b128 v[48:51], v97
	s_waitcnt lgkmcnt(0)
	v_sub_f32_e32 v48, v105, v48
	v_mul_f32_e32 v48, 0x3fb8aa3b, v48
	v_exp_f32_e32 v48, v48
	s_nop 1
	v_mul_f32_e32 v44, v44, v48
	v_sub_f32_e32 v48, v105, v49
	v_mul_f32_e32 v48, 0x3fb8aa3b, v48
	v_exp_f32_e32 v48, v48
	v_cndmask_b32_e64 v44, v44, 0, s[16:17]
	v_mul_f32_e32 v45, v45, v48
	v_sub_f32_e32 v48, v105, v50
	v_mul_f32_e32 v48, 0x3fb8aa3b, v48
	v_exp_f32_e32 v48, v48
	v_cndmask_b32_e64 v45, 0, v45, s[18:19]
	v_cvt_pk_bf16_f32 v44, v44, v45
	v_mul_f32_e32 v46, v46, v48
	v_sub_f32_e32 v48, v105, v51
	v_mul_f32_e32 v48, 0x3fb8aa3b, v48
	v_exp_f32_e32 v48, v48
	v_cndmask_b32_e64 v46, v46, 0, s[20:21]
	v_mul_f32_e32 v47, v47, v48
	v_cndmask_b32_e64 v47, v47, 0, s[22:23]
	v_cvt_pk_bf16_f32 v45, v46, v47
	ds_write_b64 v82, v[44:45] offset:9216

.LBB0_448:
	v_add_u32_e32 v105, s30, v85
	v_cvt_pk_bf16_f32 v48, v48, v49
	v_cvt_pk_bf16_f32 v49, v50, v51
	v_lshl_or_b32 v50, v105, 10, v52
	v_mov_b32_e32 v51, v53
	v_lshl_add_u64 v[50:51], v[50:51], 1, s[28:29]
	global_store_dwordx2 v[50:51], v[48:49], off offset:1024
	v_add_u32_e32 v48, s30, v86
	v_cvt_pk_bf16_f32 v44, v44, v45
	v_cvt_pk_bf16_f32 v45, v46, v47
	v_lshl_or_b32 v46, v48, 10, v52
	v_mov_b32_e32 v47, v53
	v_lshl_add_u64 v[46:47], v[46:47], 1, s[28:29]
	s_andn2_b64 vcc, exec, s[34:35]
	global_store_dwordx2 v[46:47], v[44:45], off offset:1024
	s_cbranch_vccnz .LBB0_450
	v_mov_b32_e32 v44, v68
	s_waitcnt vmcnt(8)
	v_lshlrev_b32_e32 v108, 16, v28
	v_ashrrev_i32_e32 v45, 3, v44
	v_lshlrev_b32_e32 v44, 4, v44
	v_mul_lo_u32 v105, v45, s61
	v_and_b32_e32 v116, 0x70, v44
	v_add3_u32 v117, 0, v105, v116
	v_lshl_add_u32 v44, v45, 2, 0
	ds_write_b128 v117, v[20:23]
	v_add_u32_e32 v44, 0x1f800, v44
	ds_read_b32 v118, v44
	v_and_b32_e32 v109, 0xffff0000, v28
	v_and_b32_e32 v45, 0xffff0000, v24
	v_lshlrev_b32_e32 v110, 16, v29
	v_and_b32_e32 v111, 0xffff0000, v29
	s_waitcnt lgkmcnt(0)
	v_mul_f32_e32 v44, 0x3fb8aa3b, v118
	v_exp_f32_e32 v106, v44
	v_lshlrev_b32_e32 v44, 16, v24
	v_lshlrev_b32_e32 v114, 16, v27
	v_and_b32_e32 v115, 0xffff0000, v27
	v_pk_mul_f32 v[46:47], v[106:107], v[108:109] op_sel_hi:[0,1]
	v_cvt_pk_bf16_f32 v48, v46, v47
	v_lshlrev_b32_e32 v46, 16, v25
	v_and_b32_e32 v47, 0xffff0000, v25
	v_pk_mul_f32 v[44:45], v[106:107], v[44:45] op_sel_hi:[0,1]
	v_pk_mul_f32 v[46:47], v[106:107], v[46:47] op_sel_hi:[0,1]
	v_cvt_pk_bf16_f32 v44, v44, v45
	v_cvt_pk_bf16_f32 v45, v46, v47
	v_pk_mul_f32 v[46:47], v[106:107], v[110:111] op_sel_hi:[0,1]
	v_cvt_pk_bf16_f32 v49, v46, v47
	v_lshlrev_b32_e32 v46, 16, v26
	v_and_b32_e32 v47, 0xffff0000, v26
	v_pk_mul_f32 v[46:47], v[106:107], v[46:47] op_sel_hi:[0,1]
	v_pk_mul_f32 v[114:115], v[106:107], v[114:115] op_sel_hi:[0,1]
	v_cvt_pk_bf16_f32 v46, v46, v47
	v_lshlrev_b32_e32 v112, 16, v30
	v_and_b32_e32 v113, 0xffff0000, v30
	v_cvt_pk_bf16_f32 v47, v114, v115
	v_lshlrev_b32_e32 v114, 16, v31
	v_and_b32_e32 v115, 0xffff0000, v31
	v_pk_mul_f32 v[50:51], v[106:107], v[112:113] op_sel_hi:[0,1]
	v_pk_mul_f32 v[106:107], v[106:107], v[114:115] op_sel_hi:[0,1]
	v_cvt_pk_bf16_f32 v50, v50, v51
	v_cvt_pk_bf16_f32 v51, v106, v107
	ds_write_b128 v117, v[44:47] offset:27648
	ds_write_b128 v117, v[48:51] offset:18432
	v_add3_u32 v44, s40, v105, v116
	ds_write_b128 v44, v[24:27]
	v_add3_u32 v44, s41, v105, v116
	v_readlane_b32 s4, v255, 2
	ds_write_b128 v44, v[28:31]
	s_waitcnt vmcnt(8)
	ds_write_b128 v117, v[32:35] offset:46080
	v_mov_b32_e32 v44, s4
	ds_read_b32 v44, v44
	s_waitcnt lgkmcnt(0)
	v_sub_f32_e32 v44, v44, v118
	v_mul_f32_e32 v44, 0x3fb8aa3b, v44
	v_exp_f32_e32 v48, v44
	s_nop 0
	v_pk_mul_f32 v[44:45], v[48:49], v[108:109] op_sel_hi:[0,1]
	v_pk_mul_f32 v[46:47], v[48:49], v[110:111] op_sel_hi:[0,1]
	v_cvt_pk_bf16_f32 v44, v44, v45
	v_cvt_pk_bf16_f32 v45, v46, v47
	v_pk_mul_f32 v[46:47], v[48:49], v[112:113] op_sel_hi:[0,1]
	v_pk_mul_f32 v[48:49], v[48:49], v[114:115] op_sel_hi:[0,1]
	v_cvt_pk_bf16_f32 v46, v46, v47
	v_cvt_pk_bf16_f32 v47, v48, v49
	ds_write_b128 v117, v[44:47] offset:36864
.LBB0_450:
	s_cmp_gt_u32 s48, 64
	s_waitcnt lgkmcnt(0)
	s_barrier
	s_cbranch_scc1 .Lgdn_skipB
	s_add_i32 s30, s43, 1
	s_add_i32 s31, s44, -1
	s_and_b64 s[4:5], s[26:27], exec
	s_cselect_b32 s4, s30, s31
	s_lshl_b32 s31, s4, 6
	s_add_i32 s31, s31, s2
	s_waitcnt vmcnt(8)
	v_mov_b32_e32 v20, v68
	s_and_b64 s[4:5], s[26:27], exec
	s_cselect_b32 s30, s47, s33
	v_ashrrev_i32_e32 v22, 3, v20
	s_add_i32 s30, s30, s1
	v_add_u32_e32 v21, s31, v22
	v_lshlrev_b32_e32 v20, 3, v20
	v_mul_lo_u32 v22, v22, s39
	v_and_b32_e32 v23, 56, v20
	v_add_u32_e32 v22, s30, v22
	v_or_b32_e32 v20, s0, v23
	v_mul_u32_u24_e32 v22, 0x300, v22
	v_mad_u32_u24 v20, v21, s63, v20
	v_or3_b32 v22, v22, s37, v23
	v_ashrrev_i32_e32 v21, 31, v20
	v_ashrrev_i32_e32 v23, 31, v22
	v_lshl_add_u64 v[20:21], v[20:21], 1, s[82:83]
	s_waitcnt vmcnt(8)
	v_lshl_add_u64 v[32:33], v[22:23], 1, s[84:85]
	global_load_dwordx4 v[20:23], v[20:21], off
	s_nop 0
	global_load_dwordx4 v[24:27], v[32:33], off
	global_load_dwordx4 v[28:31], v[32:33], off offset:512
	s_nop 0
	global_load_dwordx4 v[32:35], v[32:33], off offset:1024
	s_and_saveexec_b64 s[4:5], s[6:7]
	s_cbranch_execz .LBB0_426
	s_branch .LBB0_426
